# attention loops: K fragments in dedicated registers, QK reads hoisted into preceding PV section / issued at section top
# baseline (speedup 1.0000x reference)
.LBB0_519:
	s_waitcnt lgkmcnt(2)
	v_mfma_f32_32x32x16_bf16 v[50:65], v[162:165], v[86:89], v[50:65]
	ds_read_b64_tr_b16 v[94:95], v167 offset:1024
	ds_read_b64_tr_b16 v[96:97], v167 offset:3072
	ds_read_b64_tr_b16 v[86:87], v167 offset:1536
	ds_read_b64_tr_b16 v[88:89], v167 offset:3584
	v_mfma_f32_16x16x32_bf16 v[240:243], v[82:85], v[236:239], v[240:243]
	v_exp_f32_e32 v130, v130
	v_exp_f32_e32 v131, v131
	v_cndmask_b32_e64 v221, v166, v168, s[4:5]
	s_waitcnt lgkmcnt(4)
	v_mfma_f32_32x32x16_bf16 v[66:81], v[162:165], v[90:93], v[66:81]
	ds_read_b64_tr_b16 v[90:91], v167 offset:4096
	ds_read_b64_tr_b16 v[92:93], v167 offset:6144
	v_exp_f32_e32 v132, v132
	v_exp_f32_e32 v133, v133
	s_waitcnt lgkmcnt(4)
	v_mfma_f32_32x32x16_bf16 v[2:17], v[162:165], v[94:97], v[2:17]
	ds_read_b64_tr_b16 v[94:95], v167 offset:4608
	ds_read_b64_tr_b16 v[96:97], v167 offset:6656
	v_exp_f32_e32 v134, v134
	v_exp_f32_e32 v135, v135
	s_waitcnt lgkmcnt(4)
	v_mfma_f32_32x32x16_bf16 v[18:33], v[162:165], v[86:89], v[18:33]
	ds_read_b64_tr_b16 v[86:87], v167 offset:5120
	ds_read_b64_tr_b16 v[88:89], v167 offset:7168
	v_exp_f32_e32 v136, v136
	v_exp_f32_e32 v137, v137
	s_waitcnt lgkmcnt(4)
	v_mfma_f32_32x32x16_bf16 v[50:65], v[102:105], v[90:93], v[50:65]
	ds_read_b64_tr_b16 v[90:91], v167 offset:5632
	ds_read_b64_tr_b16 v[92:93], v167 offset:7680
	v_exp_f32_e32 v138, v138
	v_exp_f32_e32 v139, v139
	s_waitcnt lgkmcnt(4)
	v_mfma_f32_32x32x16_bf16 v[66:81], v[102:105], v[94:97], v[66:81]
	ds_read_b64_tr_b16 v[94:95], v167 offset:8192
	ds_read_b64_tr_b16 v[96:97], v167 offset:10240
	v_exp_f32_e32 v140, v140
	v_exp_f32_e32 v141, v141
	s_waitcnt lgkmcnt(4)
	v_mfma_f32_32x32x16_bf16 v[2:17], v[102:105], v[86:89], v[2:17]
	ds_read_b64_tr_b16 v[86:87], v167 offset:8704
	ds_read_b64_tr_b16 v[88:89], v167 offset:10752
	v_exp_f32_e32 v142, v142
	v_exp_f32_e32 v143, v143
	s_waitcnt lgkmcnt(4)
	v_mfma_f32_32x32x16_bf16 v[18:33], v[102:105], v[90:93], v[18:33]
	ds_read_b64_tr_b16 v[90:91], v167 offset:9216
	ds_read_b64_tr_b16 v[92:93], v167 offset:11264
	v_exp_f32_e32 v144, v144
	v_exp_f32_e32 v145, v145
	s_waitcnt lgkmcnt(4)
	v_mfma_f32_32x32x16_bf16 v[50:65], v[98:101], v[94:97], v[50:65]
	ds_read_b64_tr_b16 v[94:95], v167 offset:9728
	ds_read_b64_tr_b16 v[96:97], v167 offset:11776
	v_exp_f32_e32 v114, v114
	v_exp_f32_e32 v115, v115
	s_waitcnt lgkmcnt(4)
	v_mfma_f32_32x32x16_bf16 v[66:81], v[98:101], v[86:89], v[66:81]
	ds_read_b64_tr_b16 v[86:87], v167 offset:12288
	ds_read_b64_tr_b16 v[88:89], v167 offset:14336
	v_exp_f32_e32 v116, v116
	v_exp_f32_e32 v117, v117
	s_waitcnt lgkmcnt(4)
	v_mfma_f32_32x32x16_bf16 v[2:17], v[98:101], v[90:93], v[2:17]
	ds_read_b64_tr_b16 v[90:91], v167 offset:12800
	ds_read_b64_tr_b16 v[92:93], v167 offset:14848
	v_exp_f32_e32 v118, v118
	v_exp_f32_e32 v119, v119
	s_waitcnt lgkmcnt(4)
	v_mfma_f32_32x32x16_bf16 v[18:33], v[98:101], v[94:97], v[18:33]
	ds_read_b64_tr_b16 v[94:95], v167 offset:13312
	ds_read_b64_tr_b16 v[96:97], v167 offset:15360
	s_add_i32 s98, s14, 1
	s_cmp_lg_u32 s14, 4
	s_cselect_b32 s98, s98, 0
	v_lshl_add_u32 v252, s98, 13, v205
	ds_read_b128 v[244:247], v252
	ds_read_b128 v[248:251], v252 offset:512
	v_exp_f32_e32 v120, v120
	v_exp_f32_e32 v121, v121
	s_waitcnt lgkmcnt(6)
	v_mfma_f32_32x32x16_bf16 v[50:65], v[82:85], v[86:89], v[50:65]
	ds_read_b64_tr_b16 v[86:87], v167 offset:13824
	ds_read_b64_tr_b16 v[88:89], v167 offset:15872
	v_exp_f32_e32 v122, v122
	v_exp_f32_e32 v123, v123
	s_waitcnt lgkmcnt(6)
	v_mfma_f32_32x32x16_bf16 v[66:81], v[82:85], v[90:93], v[66:81]
	v_exp_f32_e32 v124, v124
	v_exp_f32_e32 v125, v125
	s_waitcnt lgkmcnt(4)
	v_mfma_f32_32x32x16_bf16 v[2:17], v[82:85], v[94:97], v[2:17]
	v_exp_f32_e32 v126, v126
	v_exp_f32_e32 v127, v127
	s_waitcnt lgkmcnt(0)
	v_mfma_f32_32x32x16_bf16 v[18:33], v[82:85], v[86:89], v[18:33]
	v_exp_f32_e32 v128, v128
	v_exp_f32_e32 v129, v129
	s_add_i32 s4, s14, -4
	s_add_i32 s9, s14, 1
	s_cmp_gt_i32 s14, 3
	s_cselect_b32 s4, s4, s9
	v_lshl_add_u32 v86, s4, 13, v205
	s_add_i32 s4, s66, 0xffffff42
	s_cmpk_lt_i32 s4, 0xff42
	s_cselect_b64 vcc, -1, 0
	s_cmpk_gt_i32 s4, 0x9e
	s_cselect_b64 s[4:5], -1, 0
	v_cndmask_b32_e64 v86, 0, v207, s[4:5]
	v_cndmask_b32_e32 v223, v86, v206, vcc
	v_cmp_eq_f32_e32 vcc, v223, v221
	v_cmp_neq_f32_e64 s[4:5], v223, v221
	s_cbranch_vccnz .LBB0_521
	v_sub_f32_e32 v34, v223, v217
	v_mov_b32_e32 v35, v34
	v_mov_b32_e32 v36, v34
	v_mov_b32_e32 v37, v34
	v_mov_b32_e32 v38, v34
	v_mov_b32_e32 v39, v34
	v_mov_b32_e32 v40, v34
	v_mov_b32_e32 v41, v34
	v_mov_b32_e32 v42, v34
	v_mov_b32_e32 v43, v34
	v_mov_b32_e32 v44, v34
	v_mov_b32_e32 v45, v34
	v_mov_b32_e32 v46, v34
	v_mov_b32_e32 v47, v34
	v_mov_b32_e32 v48, v34
	v_mov_b32_e32 v49, v34
.LBB0_521:
	s_cmp_lg_u32 s14, 4
	s_cselect_b32 s9, s9, 0
	s_lshl_b32 s12, s14, 14
	s_cmpk_gt_u32 s66, 0x15c
	v_add_u32_e32 v222, s12, v204
	v_lshl_add_u32 v228, s9, 13, v205
	v_mfma_f32_32x32x16_bf16 v[98:113], v[244:247], v[158:161], v[34:49]
	ds_read_b128 v[224:227], v228 offset:2048
	v_cvt_pk_bf16_f32 v162, v130, v131
	v_cvt_pk_bf16_f32 v163, v132, v133
	s_nop 0
	ds_read_b128 v[130:133], v228 offset:2560
	v_cvt_pk_bf16_f32 v164, v134, v135
	v_cvt_pk_bf16_f32 v165, v136, v137
	v_mfma_f32_32x32x16_bf16 v[82:97], v[248:251], v[158:161], v[34:49]
	s_waitcnt lgkmcnt(1)
	v_mfma_f32_32x32x16_bf16 v[98:113], v[224:227], v[154:157], v[98:113]
	ds_read_b128 v[166:169], v228 offset:4096
	v_mfma_f32_16x16x32_bf16 v[240:243], v[162:165], v[236:239], v[240:243]
	v_cvt_pk_bf16_f32 v134, v138, v139
	v_cvt_pk_bf16_f32 v135, v140, v141
	s_waitcnt lgkmcnt(1)
	v_mfma_f32_32x32x16_bf16 v[82:97], v[130:133], v[154:157], v[82:97]
	ds_read_b128 v[138:141], v228 offset:4608
	v_cvt_pk_bf16_f32 v136, v142, v143
	v_cvt_pk_bf16_f32 v137, v144, v145
	s_waitcnt lgkmcnt(1)
	v_mfma_f32_32x32x16_bf16 v[98:113], v[166:169], v[150:153], v[98:113]
	ds_read_b128 v[142:145], v228 offset:6144
	v_mfma_f32_16x16x32_bf16 v[240:243], v[134:137], v[236:239], v[240:243]
	v_cvt_pk_bf16_f32 v130, v114, v115
	v_cvt_pk_bf16_f32 v131, v116, v117
	s_waitcnt lgkmcnt(1)
	v_mfma_f32_32x32x16_bf16 v[82:97], v[138:141], v[150:153], v[82:97]
	ds_read_b128 v[166:169], v228 offset:6656
	v_cvt_pk_bf16_f32 v132, v118, v119
	v_cvt_pk_bf16_f32 v133, v120, v121
	s_waitcnt lgkmcnt(1)
	v_mfma_f32_32x32x16_bf16 v[98:113], v[142:145], v[146:149], v[98:113]
	v_cvt_pk_bf16_f32 v114, v122, v123
	v_mfma_f32_16x16x32_bf16 v[240:243], v[130:133], v[236:239], v[240:243]
	v_cvt_pk_bf16_f32 v115, v124, v125
	ds_read_b64_tr_b16 v[122:123], v222
	ds_read_b64_tr_b16 v[124:125], v222 offset:2048
	s_waitcnt lgkmcnt(2)
	v_mfma_f32_32x32x16_bf16 v[82:97], v[166:169], v[146:149], v[82:97]
	v_cvt_pk_bf16_f32 v116, v126, v127
	v_cvt_pk_bf16_f32 v117, v128, v129
	ds_read_b64_tr_b16 v[118:119], v222 offset:512
	ds_read_b64_tr_b16 v[120:121], v222 offset:2560
	s_cbranch_scc1 .LBB0_512
	ds_read2_b32 v[126:127], v218 offset0:64 offset1:65
	ds_read2_b32 v[128:129], v218 offset0:96 offset1:97
	ds_read2_b32 v[138:139], v218 offset0:66 offset1:67
	ds_read2_b32 v[140:141], v218 offset0:98 offset1:99
	ds_read2_b32 v[142:143], v218 offset0:72 offset1:73
	ds_read2_b32 v[144:145], v218 offset0:104 offset1:105
	ds_read2_b32 v[166:167], v218 offset0:74 offset1:75
	ds_read2_b32 v[168:169], v218 offset0:106 offset1:107
	s_waitcnt lgkmcnt(7)
	v_pk_add_f32 v[98:99], v[98:99], v[126:127]
	ds_read2_b32 v[224:225], v218 offset0:80 offset1:81
	s_waitcnt lgkmcnt(7)
	v_pk_add_f32 v[82:83], v[82:83], v[128:129]
	ds_read2_b32 v[226:227], v218 offset0:112 offset1:113
	s_waitcnt lgkmcnt(7)
	v_pk_add_f32 v[100:101], v[100:101], v[138:139]
	ds_read2_b32 v[228:229], v218 offset0:82 offset1:83
	s_waitcnt lgkmcnt(7)
	v_pk_add_f32 v[84:85], v[84:85], v[140:141]
	ds_read2_b32 v[244:245], v218 offset0:114 offset1:115
	s_waitcnt lgkmcnt(7)
	v_pk_add_f32 v[102:103], v[142:143], v[102:103]
	ds_read2_b32 v[246:247], v218 offset0:88 offset1:89
	s_waitcnt lgkmcnt(7)
	v_pk_add_f32 v[86:87], v[86:87], v[144:145]
	ds_read2_b32 v[248:249], v218 offset0:120 offset1:121
	s_waitcnt lgkmcnt(7)
	v_pk_add_f32 v[104:105], v[104:105], v[166:167]
	ds_read2_b32 v[250:251], v218 offset0:90 offset1:91
	s_waitcnt lgkmcnt(7)
	v_pk_add_f32 v[88:89], v[88:89], v[168:169]
	ds_read2_b32 v[252:253], v218 offset0:122 offset1:123
	s_waitcnt lgkmcnt(7)
	v_pk_add_f32 v[106:107], v[224:225], v[106:107]
	s_waitcnt lgkmcnt(6)
	v_pk_add_f32 v[90:91], v[90:91], v[226:227]
	s_waitcnt lgkmcnt(5)
	v_pk_add_f32 v[108:109], v[108:109], v[228:229]
	s_waitcnt lgkmcnt(4)
	v_pk_add_f32 v[92:93], v[92:93], v[244:245]
	s_waitcnt lgkmcnt(3)
	v_pk_add_f32 v[110:111], v[246:247], v[110:111]
	s_waitcnt lgkmcnt(2)
	v_pk_add_f32 v[94:95], v[94:95], v[248:249]
	s_waitcnt lgkmcnt(1)
	v_pk_add_f32 v[112:113], v[112:113], v[250:251]
	s_waitcnt lgkmcnt(0)
	v_pk_add_f32 v[96:97], v[96:97], v[252:253]
	s_nop 0
	s_branch .LBB0_512

.LBB0_590:
	s_waitcnt lgkmcnt(2)
	v_mfma_f32_32x32x16_bf16 v[16:31], v[128:131], v[48:51], v[16:31]
	ds_read_b64_tr_b16 v[56:57], v15 offset:2048
	ds_read_b64_tr_b16 v[58:59], v15 offset:3072
	ds_read_b64_tr_b16 v[48:49], v15 offset:2560
	ds_read_b64_tr_b16 v[50:51], v15 offset:3584
	v_mfma_f32_16x16x32_bf16 v[144:147], v[2:5], v[140:143], v[144:147]
	v_exp_f32_e32 v96, v96
	v_exp_f32_e32 v97, v97
	v_exp_f32_e32 v98, v98
	v_exp_f32_e32 v99, v99
	s_waitcnt lgkmcnt(4)
	v_mfma_f32_32x32x16_bf16 v[32:47], v[128:131], v[52:55], v[32:47]
	ds_read_b64_tr_b16 v[52:53], v15 offset:4096
	ds_read_b64_tr_b16 v[54:55], v15 offset:5120
	s_add_i32 s98, s8, 1
	s_cmp_lg_u32 s8, 4
	s_cselect_b32 s98, s98, 0
	v_lshl_add_u32 v188, s98, 13, v135
	ds_read_b128 v[156:159], v188
	ds_read_b128 v[160:163], v188 offset:512
	v_exp_f32_e32 v100, v100
	v_exp_f32_e32 v101, v101
	v_exp_f32_e32 v102, v102
	v_exp_f32_e32 v103, v103
	s_waitcnt lgkmcnt(6)
	v_mfma_f32_32x32x16_bf16 v[16:31], v[10:13], v[56:59], v[16:31]
	ds_read_b64_tr_b16 v[56:57], v15 offset:4608
	ds_read_b64_tr_b16 v[58:59], v15 offset:5632
	ds_read_b128 v[164:167], v188 offset:2048
	v_exp_f32_e32 v104, v104
	v_exp_f32_e32 v105, v105
	v_exp_f32_e32 v106, v106
	v_exp_f32_e32 v107, v107
	s_waitcnt lgkmcnt(7)
	v_mfma_f32_32x32x16_bf16 v[32:47], v[10:13], v[48:51], v[32:47]
	ds_read_b64_tr_b16 v[10:11], v15 offset:6144
	ds_read_b64_tr_b16 v[12:13], v15 offset:7168
	ds_read_b128 v[168:171], v188 offset:2560
	v_exp_f32_e32 v108, v108
	v_exp_f32_e32 v109, v109
	v_exp_f32_e32 v110, v110
	v_exp_f32_e32 v111, v111
	s_waitcnt lgkmcnt(8)
	v_mfma_f32_32x32x16_bf16 v[16:31], v[6:9], v[52:55], v[16:31]
	ds_read_b64_tr_b16 v[48:49], v15 offset:6656
	ds_read_b64_tr_b16 v[50:51], v15 offset:7680
	ds_read_b128 v[172:175], v188 offset:4096
	v_exp_f32_e32 v80, v80
	v_exp_f32_e32 v81, v81
	v_exp_f32_e32 v82, v82
	v_exp_f32_e32 v83, v83
	s_waitcnt lgkmcnt(7)
	v_mfma_f32_32x32x16_bf16 v[32:47], v[6:9], v[56:59], v[32:47]
	ds_read_b128 v[176:179], v188 offset:4608
	v_exp_f32_e32 v84, v84
	v_exp_f32_e32 v85, v85
	v_exp_f32_e32 v86, v86
	v_exp_f32_e32 v87, v87
	s_waitcnt lgkmcnt(5)
	v_mfma_f32_32x32x16_bf16 v[16:31], v[2:5], v[10:13], v[16:31]
	ds_read_b128 v[180:183], v188 offset:6144
	v_exp_f32_e32 v88, v88
	v_exp_f32_e32 v89, v89
	v_exp_f32_e32 v90, v90
	v_exp_f32_e32 v91, v91
	s_waitcnt lgkmcnt(3)
	v_mfma_f32_32x32x16_bf16 v[32:47], v[2:5], v[48:51], v[32:47]
	ds_read_b128 v[184:187], v188 offset:6656
	v_exp_f32_e32 v92, v92
	v_exp_f32_e32 v93, v93
	v_exp_f32_e32 v94, v94
	v_exp_f32_e32 v95, v95
	s_add_i32 s12, s8, -4
	s_add_i32 s13, s8, 1
	s_cmp_gt_i32 s8, 3
	s_cselect_b32 s12, s12, s13
	v_lshl_add_u32 v6, s12, 13, v135
	s_cmp_lg_u32 s8, 4
	s_cselect_b32 s54, s13, 0
	v_lshl_add_u32 v15, s54, 13, v135
	v_lshl_add_u32 v128, s8, 14, v1
	v_mfma_f32_32x32x16_bf16 v[64:79], v[156:159], v[124:127], 0
	v_cvt_pk_bf16_f32 v2, v96, v97
	v_cvt_pk_bf16_f32 v3, v98, v99
	s_nop 0
	v_cvt_pk_bf16_f32 v4, v100, v101
	v_mfma_f32_32x32x16_bf16 v[48:63], v[160:163], v[124:127], 0
	v_cvt_pk_bf16_f32 v5, v102, v103
	v_mfma_f32_32x32x16_bf16 v[64:79], v[164:167], v[120:123], v[64:79]
	v_mfma_f32_16x16x32_bf16 v[144:147], v[2:5], v[140:143], v[144:147]
	v_cvt_pk_bf16_f32 v10, v104, v105
	v_cvt_pk_bf16_f32 v11, v106, v107
	v_mfma_f32_32x32x16_bf16 v[48:63], v[168:171], v[120:123], v[48:63]
	v_cvt_pk_bf16_f32 v12, v108, v109
	v_cvt_pk_bf16_f32 v13, v110, v111
	s_waitcnt lgkmcnt(3)
	v_mfma_f32_32x32x16_bf16 v[64:79], v[172:175], v[116:119], v[64:79]
	v_mfma_f32_16x16x32_bf16 v[144:147], v[10:13], v[140:143], v[144:147]
	v_cvt_pk_bf16_f32 v6, v80, v81
	v_cvt_pk_bf16_f32 v7, v82, v83
	s_waitcnt lgkmcnt(2)
	v_mfma_f32_32x32x16_bf16 v[48:63], v[176:179], v[116:119], v[48:63]
	v_cvt_pk_bf16_f32 v8, v84, v85
	v_cvt_pk_bf16_f32 v9, v86, v87
	s_waitcnt lgkmcnt(1)
	v_mfma_f32_32x32x16_bf16 v[64:79], v[180:183], v[112:115], v[64:79]
	v_mfma_f32_16x16x32_bf16 v[144:147], v[6:9], v[140:143], v[144:147]
	v_cvt_pk_bf16_f32 v84, v88, v89
	v_cvt_pk_bf16_f32 v85, v90, v91
	ds_read_b64_tr_b16 v[88:89], v128
	ds_read_b64_tr_b16 v[90:91], v128 offset:1024
	s_waitcnt lgkmcnt(2)
	v_mfma_f32_32x32x16_bf16 v[48:63], v[184:187], v[112:115], v[48:63]
	v_cvt_pk_bf16_f32 v86, v92, v93
	v_cvt_pk_bf16_f32 v87, v94, v95
	ds_read_b64_tr_b16 v[80:81], v128 offset:512
	ds_read_b64_tr_b16 v[82:83], v128 offset:1536
	s_waitcnt lgkmcnt(2)
	v_mfma_f32_32x32x16_bf16 v[16:31], v[2:5], v[88:91], v[16:31]
	ds_read_b64_tr_b16 v[92:93], v128 offset:2048
	ds_read_b64_tr_b16 v[94:95], v128 offset:3072
	ds_read_b64_tr_b16 v[88:89], v128 offset:2560
	ds_read_b64_tr_b16 v[90:91], v128 offset:3584
	v_mfma_f32_16x16x32_bf16 v[144:147], v[84:87], v[140:143], v[144:147]
	v_exp_f32_e32 v64, v64
	v_exp_f32_e32 v65, v65
	v_exp_f32_e32 v66, v66
	v_exp_f32_e32 v67, v67
	s_waitcnt lgkmcnt(4)
	v_mfma_f32_32x32x16_bf16 v[32:47], v[2:5], v[80:83], v[32:47]
	ds_read_b64_tr_b16 v[2:3], v128 offset:4096
	ds_read_b64_tr_b16 v[4:5], v128 offset:5120
	v_exp_f32_e32 v68, v68
	v_exp_f32_e32 v69, v69
	v_exp_f32_e32 v70, v70
	v_exp_f32_e32 v71, v71
	s_waitcnt lgkmcnt(4)
	v_mfma_f32_32x32x16_bf16 v[16:31], v[10:13], v[92:95], v[16:31]
	ds_read_b64_tr_b16 v[80:81], v128 offset:4608
	ds_read_b64_tr_b16 v[82:83], v128 offset:5632
	v_exp_f32_e32 v72, v72
	v_exp_f32_e32 v73, v73
	v_exp_f32_e32 v74, v74
	v_exp_f32_e32 v75, v75
	s_waitcnt lgkmcnt(4)
	v_mfma_f32_32x32x16_bf16 v[32:47], v[10:13], v[88:91], v[32:47]
	ds_read_b64_tr_b16 v[10:11], v128 offset:6144
	ds_read_b64_tr_b16 v[12:13], v128 offset:7168
	v_exp_f32_e32 v76, v76
	v_exp_f32_e32 v77, v77
	v_exp_f32_e32 v78, v78
	v_exp_f32_e32 v79, v79
	s_waitcnt lgkmcnt(4)
	v_mfma_f32_32x32x16_bf16 v[16:31], v[6:9], v[2:5], v[16:31]
	ds_read_b64_tr_b16 v[2:3], v128 offset:6656
	ds_read_b64_tr_b16 v[4:5], v128 offset:7680
	v_exp_f32_e32 v48, v48
	v_exp_f32_e32 v49, v49
	v_exp_f32_e32 v50, v50
	v_exp_f32_e32 v51, v51
	s_waitcnt lgkmcnt(4)
	v_mfma_f32_32x32x16_bf16 v[32:47], v[6:9], v[80:83], v[32:47]
	v_exp_f32_e32 v52, v52
	v_exp_f32_e32 v53, v53
	v_exp_f32_e32 v54, v54
	v_exp_f32_e32 v55, v55
	s_waitcnt lgkmcnt(2)
	v_mfma_f32_32x32x16_bf16 v[16:31], v[84:87], v[10:13], v[16:31]
	v_exp_f32_e32 v56, v56
	v_exp_f32_e32 v57, v57
	v_exp_f32_e32 v58, v58
	v_exp_f32_e32 v59, v59
	s_waitcnt lgkmcnt(0)
	v_mfma_f32_32x32x16_bf16 v[32:47], v[84:87], v[2:5], v[32:47]
	v_exp_f32_e32 v60, v60
	v_exp_f32_e32 v61, v61
	v_exp_f32_e32 v62, v62
	v_exp_f32_e32 v63, v63
	s_add_i32 s8, s54, 1
	s_cmp_lg_u32 s54, 4
	s_cselect_b32 s8, s8, 0
	s_add_u32 s6, s6, 0x4000
	s_addc_u32 s7, s7, 0
	s_add_u32 s40, s40, 0x4000
	s_waitcnt vmcnt(0) lgkmcnt(0)
	s_barrier
	s_addc_u32 s41, s41, 0
	s_add_i32 s49, s49, 2
	s_cmp_lt_u32 s51, s50
	s_cbranch_scc0 .LBB0_596
.LBB0_591:
	v_lshl_add_u32 v136, s8, 13, v135
	ds_read_b128 v[156:159], v136
	ds_read_b128 v[160:163], v136 offset:512
	ds_read_b128 v[164:167], v136 offset:2048
	ds_read_b128 v[168:171], v136 offset:2560
	ds_read_b128 v[172:175], v136 offset:4096
	ds_read_b128 v[176:179], v136 offset:4608
	ds_read_b128 v[180:183], v136 offset:6144
	ds_read_b128 v[184:187], v136 offset:6656
	s_lshl_b32 s12, s54, 14
	v_add_u32_e32 v15, s12, v1
	s_waitcnt lgkmcnt(7)
	v_mfma_f32_32x32x16_bf16 v[96:111], v[156:159], v[124:127], 0
	v_cvt_pk_bf16_f32 v128, v64, v65
	v_cvt_pk_bf16_f32 v129, v66, v67
	s_waitcnt lgkmcnt(6)
	v_mfma_f32_32x32x16_bf16 v[80:95], v[160:163], v[124:127], 0
	v_cvt_pk_bf16_f32 v130, v68, v69
	v_cvt_pk_bf16_f32 v131, v70, v71
	s_waitcnt lgkmcnt(5)
	v_mfma_f32_32x32x16_bf16 v[96:111], v[164:167], v[120:123], v[96:111]
	v_mfma_f32_16x16x32_bf16 v[144:147], v[128:131], v[140:143], v[144:147]
	v_cvt_pk_bf16_f32 v10, v72, v73
	v_cvt_pk_bf16_f32 v11, v74, v75
	s_waitcnt lgkmcnt(4)
	v_mfma_f32_32x32x16_bf16 v[80:95], v[168:171], v[120:123], v[80:95]
	v_cvt_pk_bf16_f32 v12, v76, v77
	v_cvt_pk_bf16_f32 v13, v78, v79
	s_waitcnt lgkmcnt(3)
	v_mfma_f32_32x32x16_bf16 v[96:111], v[172:175], v[116:119], v[96:111]
	v_mfma_f32_16x16x32_bf16 v[144:147], v[10:13], v[140:143], v[144:147]
	v_cvt_pk_bf16_f32 v6, v48, v49
	v_cvt_pk_bf16_f32 v7, v50, v51
	s_waitcnt lgkmcnt(2)
	v_mfma_f32_32x32x16_bf16 v[80:95], v[176:179], v[116:119], v[80:95]
	v_cvt_pk_bf16_f32 v8, v52, v53
	v_cvt_pk_bf16_f32 v9, v54, v55
	s_waitcnt lgkmcnt(1)
	v_mfma_f32_32x32x16_bf16 v[96:111], v[180:183], v[112:115], v[96:111]
	v_mfma_f32_16x16x32_bf16 v[144:147], v[6:9], v[140:143], v[144:147]
	v_cvt_pk_bf16_f32 v2, v56, v57
	v_cvt_pk_bf16_f32 v3, v58, v59
	ds_read_b64_tr_b16 v[48:49], v15
	ds_read_b64_tr_b16 v[50:51], v15 offset:1024
	s_waitcnt lgkmcnt(2)
	v_mfma_f32_32x32x16_bf16 v[80:95], v[184:187], v[112:115], v[80:95]
	v_cvt_pk_bf16_f32 v4, v60, v61
	v_cvt_pk_bf16_f32 v5, v62, v63
	ds_read_b64_tr_b16 v[52:53], v15 offset:512
	ds_read_b64_tr_b16 v[54:55], v15 offset:1536
	s_add_i32 s51, s49, -1
	s_cmp_ge_u32 s51, s48
	s_cbranch_scc1 .LBB0_593
	s_add_u32 s12, s40, 0xffffe000
	s_addc_u32 s13, s41, -1
	s_cmp_gt_i32 s8, 2
	s_cselect_b32 s54, -3, 2
	s_add_i32 s54, s54, s8
	s_lshl_b32 s55, s54, 13
	s_add_i32 s55, s55, s46
	s_mov_b32 s56, m0
	s_mov_b32 m0, s55
	s_nop 0
	global_load_lds_dwordx4 v134, s[12:13]
	s_mov_b32 m0, s56
	s_add_u32 s12, s6, 0xffffe000
	s_addc_u32 s13, s7, -1
	s_lshl_b32 s54, s54, 14
	s_add_i32 s54, s54, s47
	s_mov_b32 s55, m0
	s_mov_b32 m0, s54
	s_nop 0
	global_load_lds_dwordx4 v134, s[12:13]
	s_mov_b32 m0, s55
